# late weight copies (P4 tail) also staged through LDS for full-line stores; vmcnt counts adjusted
# speedup vs baseline: 1.0186x; 1.0071x over previous
; __device__ __forceinline__ unsigned pk2(float lo, float hi) { typedef float f2_t __attribute__((ext_vector_type(2))); typedef __bf16 b2_t __attribute__((ext_vector_type(2))); const f2_t v = {lo, hi}; return __builtin_bit_cast(unsigned, __builtin_convertvector(v, b2_t)); }
; __device__ __forceinline__ void transpose_item(const float* W, int K, int N, bf16* WT, int mode, int row_off, const float* gain, int item, int lane) {
;     ...
;     bf16* dst = WT + (size_t)(rbase + lane) * K + k0;
; #pragma unroll
;     for (int c = 0; c < 8; ++c) { v4u o; o.x = pk2(v[8 * c], v[8 * c + 1]); o.y = pk2(v[8 * c + 2], v[8 * c + 3]); o.z = pk2(v[8 * c + 4], v[8 * c + 5]); o.w = pk2(v[8 * c + 6], v[8 * c + 7]);
;         *(v4u*)(dst + 8 * c) = o; }
.LBB0_296:
	s_waitcnt vmcnt(54)
	v_cvt_pk_bf16_f32 v2, v2, v3
	s_waitcnt vmcnt(52)
	v_cvt_pk_bf16_f32 v3, v4, v5
	s_waitcnt vmcnt(50)
	v_cvt_pk_bf16_f32 v4, v6, v7
	s_waitcnt vmcnt(48)
	v_cvt_pk_bf16_f32 v5, v8, v9
	ds_write_b128 v200, v[2:5] offset:16
	s_nop 1
	s_mov_b64 s[74:75], 0
	s_waitcnt vmcnt(46)
	v_cvt_pk_bf16_f32 v2, v10, v11
	s_waitcnt vmcnt(44)
	v_cvt_pk_bf16_f32 v3, v12, v13
	s_waitcnt vmcnt(42)
	v_cvt_pk_bf16_f32 v4, v14, v15
	s_waitcnt vmcnt(40)
	v_cvt_pk_bf16_f32 v5, v16, v17
	ds_write_b128 v200, v[2:5] offset:32
	s_nop 1
	s_waitcnt vmcnt(38)
	s_nop 0
	v_cvt_pk_bf16_f32 v2, v18, v19
	s_waitcnt vmcnt(36)
	v_cvt_pk_bf16_f32 v3, v20, v21
	s_waitcnt vmcnt(34)
	v_cvt_pk_bf16_f32 v4, v22, v23
	s_waitcnt vmcnt(32)
	v_cvt_pk_bf16_f32 v5, v24, v25
	ds_write_b128 v200, v[2:5] offset:48
	s_nop 1
	s_waitcnt vmcnt(30)
	s_nop 0
	v_cvt_pk_bf16_f32 v2, v26, v27
	s_waitcnt vmcnt(28)
	v_cvt_pk_bf16_f32 v3, v28, v29
	s_waitcnt vmcnt(26)
	v_cvt_pk_bf16_f32 v4, v30, v31
	s_waitcnt vmcnt(24)
	v_cvt_pk_bf16_f32 v5, v32, v33
	ds_write_b128 v200, v[2:5] offset:64
	s_nop 1
	s_waitcnt vmcnt(22)
	s_nop 0
	v_cvt_pk_bf16_f32 v2, v34, v35
	s_waitcnt vmcnt(20)
	v_cvt_pk_bf16_f32 v3, v36, v37
	s_waitcnt vmcnt(18)
	v_cvt_pk_bf16_f32 v4, v38, v39
	s_waitcnt vmcnt(16)
	v_cvt_pk_bf16_f32 v5, v40, v41
	ds_write_b128 v200, v[2:5] offset:80
	s_nop 1
	s_waitcnt vmcnt(14)
	s_nop 0
	v_cvt_pk_bf16_f32 v2, v42, v43
	s_waitcnt vmcnt(12)
	v_cvt_pk_bf16_f32 v3, v44, v45
	s_waitcnt vmcnt(10)
	v_cvt_pk_bf16_f32 v4, v46, v47
	s_waitcnt vmcnt(8)
	v_cvt_pk_bf16_f32 v5, v48, v49
	ds_write_b128 v200, v[2:5] offset:96
	s_nop 1
	s_waitcnt vmcnt(6)
	s_nop 0
	v_cvt_pk_bf16_f32 v2, v50, v51
	s_waitcnt vmcnt(4)
	v_cvt_pk_bf16_f32 v3, v52, v53
	s_waitcnt vmcnt(2)
	v_cvt_pk_bf16_f32 v4, v54, v55
	s_waitcnt vmcnt(0)
	v_cvt_pk_bf16_f32 v5, v56, v57
	ds_write_b128 v200, v[2:5] offset:112
	s_nop 1
	v_lshrrev_b32_e32 v202, 3, v188
	v_and_b32_e32 v203, 7, v188
	v_lshrrev_b32_e32 v201, 6, v189
	v_lshlrev_b32_e32 v203, 4, v203
	v_mul_u32_u24_e32 v201, 0x2400, v201
	v_mul_u32_u24_e32 v204, 0x90, v202
	v_add3_u32 v201, v201, v204, v203
	ds_read_b128 v[208:211], v201
	ds_read_b128 v[212:215], v201 offset:1152
	ds_read_b128 v[216:219], v201 offset:2304
	ds_read_b128 v[220:223], v201 offset:3456
	ds_read_b128 v[224:227], v201 offset:4608
	ds_read_b128 v[228:231], v201 offset:5760
	ds_read_b128 v[232:235], v201 offset:6912
	ds_read_b128 v[236:239], v201 offset:8064
	v_readlane_b32 s82, v58, 0
	v_readlane_b32 s83, v59, 0
	v_readlane_b32 vcc_lo, v58, 1
	s_nop 1
	v_mov_b32_e32 v205, vcc_lo
	v_subrev_u32_e32 v205, s82, v205
	v_mul_lo_u32 v206, v202, v205
	v_add_u32_e32 v206, v206, v203
	v_lshlrev_b32_e32 v205, 3, v205
	s_waitcnt lgkmcnt(0)
	global_store_dwordx4 v206, v[208:211], s[82:83]
	v_add_u32_e32 v207, v206, v205
	global_store_dwordx4 v207, v[212:215], s[82:83]
	v_add_u32_e32 v206, v207, v205
	global_store_dwordx4 v206, v[216:219], s[82:83]
	v_add_u32_e32 v207, v206, v205
	global_store_dwordx4 v207, v[220:223], s[82:83]
	v_add_u32_e32 v206, v207, v205
	global_store_dwordx4 v206, v[224:227], s[82:83]
	v_add_u32_e32 v207, v206, v205
	global_store_dwordx4 v207, v[228:231], s[82:83]
	v_add_u32_e32 v206, v207, v205
	global_store_dwordx4 v206, v[232:235], s[82:83]
	v_add_u32_e32 v207, v206, v205
	global_store_dwordx4 v207, v[236:239], s[82:83]

; __device__ __forceinline__ void transpose_item(const float* W, int K, int N, bf16* WT, int mode, int row_off, const float* gain, int item, int lane) {
;     const int nblk = N / 64, kb = item / nblk, nb = item % nblk, k0 = 64 * kb, n0 = 64 * nb;
;     const int rbase = (mode == 0) ? (row_off + n0) : ((n0 >> 7) * 256 + (n0 & 127) + row_off);
;     const float* src = W + (size_t)k0 * N + n0 + lane;
;     float v[64];
; #pragma unroll
;     for (int i = 0; i < 64; ++i) v[i] = src[(size_t)i * N];
; __global__ void __launch_bounds__(NWAVES * 64, 2) hybrid_fwd(Args args) {
;     ...
;                 t = __builtin_amdgcn_readfirstlane(t);
;                 if (t >= N_LATE / 8) break;
;                 int r = t * 8 + qi;
;                 if (r < IT_P) { transpose_item(args.in[I_PA], AW, D, (bf16*)(ws + WS_PA), 0, 0, nullptr, r, lane); continue; } r -= IT_P;
;                 if (r < IT_P) { transpose_item(args.in[I_PB], SW, D, (bf16*)(ws + WS_PB), 0, 0, nullptr, r, lane); continue; } r -= IT_P;
;                 if (r < IT_O) { transpose_item(args.in[I_WOUT], D, D, (bf16*)(ws + WS_WOUT), 0, 0, nullptr, r, lane); continue; } r -= IT_O;
;                 if (r < IT_FF) { transpose_item(args.in[I_WG2], D, FF, (bf16*)(ws + WS_WGU2), 1, 0, args.in[I_N2], r, lane); continue; } r -= IT_FF;
;                 if (r < IT_FF) { transpose_item(args.in[I_WU2], D, FF, (bf16*)(ws + WS_WGU2), 1, 128, args.in[I_N2], r, lane); continue; } r -= IT_FF;
;                 transpose_item(args.in[I_WD2], FF, D, (bf16*)(ws + WS_WD2), 0, 0, nullptr, r, lane);
.LBB0_302:
	s_or_b64 exec, exec, s[74:75]
	v_readfirstlane_b32 s81, v2
	s_cmpk_gt_i32 s81, 0x51f
	s_mov_b64 s[74:75], -1
	s_cbranch_scc1 .LBB0_297
	s_lshl_b32 s66, s81, 3
	s_or_b32 s80, s66, s12
	s_cmpk_gt_i32 s80, 0x1ff
	s_cbranch_scc0 .LBB0_325
	s_cmpk_gt_u32 s66, 0x3ff
	s_cbranch_scc0 .LBB0_322
	s_cmpk_gt_u32 s66, 0x7ff
	s_cbranch_scc0 .LBB0_319
	s_cmpk_gt_u32 s66, 0x12ff
	s_cbranch_scc0 .LBB0_314
	s_cmpk_gt_u32 s66, 0x1dff
	s_cbranch_scc0 .LBB0_309
	s_lshl_b32 s66, s81, 4
	s_andn2_b32 s66, s66, 63
	s_addk_i32 s66, 0xc400
	s_lshl_b32 s74, s80, 6
	v_readlane_b32 s44, v254, 48
	s_and_b32 s74, s74, 0x7c0
	s_lshl_b64 s[82:83], s[66:67], 13
	v_readlane_b32 s52, v254, 56
	v_readlane_b32 s53, v254, 57
	s_add_u32 s75, s52, s82
	s_addc_u32 s83, s53, s83
	s_lshl_b32 s82, s74, 2
	s_add_u32 s82, s75, s82
	s_addc_u32 s83, s83, 0
	v_lshl_add_u64 v[58:59], s[82:83], 0, v[0:1]
	s_movk_i32 s44, 0x2000
	v_add_co_u32_e32 v2, vcc, s44, v58
	s_movk_i32 s44, 0x4000
	s_nop 0
	v_addc_co_u32_e32 v3, vcc, 0, v59, vcc
	global_load_dword v60, v0, s[82:83]
	global_load_dword v61, v[2:3], off
	v_add_co_u32_e32 v2, vcc, s44, v58
	s_movk_i32 s44, 0x6000
	s_nop 0
	v_addc_co_u32_e32 v3, vcc, 0, v59, vcc
	global_load_dword v62, v[2:3], off
	v_add_co_u32_e32 v2, vcc, s44, v58
	s_mov_b32 s44, 0x8000
	s_nop 0
	v_addc_co_u32_e32 v3, vcc, 0, v59, vcc
	global_load_dword v63, v[2:3], off
	v_add_co_u32_e32 v2, vcc, s44, v58
	s_mov_b32 s44, 0xa000
	s_nop 0
	v_addc_co_u32_e32 v3, vcc, 0, v59, vcc
	global_load_dword v64, v[2:3], off
	v_add_co_u32_e32 v2, vcc, s44, v58
	v_readlane_b32 s45, v254, 49
	s_nop 0
	v_addc_co_u32_e32 v3, vcc, 0, v59, vcc
	global_load_dword v65, v[2:3], off
	v_add_co_u32_e32 v2, vcc, s41, v58
	v_readlane_b32 s44, v255, 25
	s_nop 0
	v_addc_co_u32_e32 v3, vcc, 0, v59, vcc
	global_load_dword v66, v[2:3], off
	v_add_co_u32_e32 v2, vcc, s69, v58
	v_readlane_b32 s45, v255, 26
	s_nop 0
	v_addc_co_u32_e32 v3, vcc, 0, v59, vcc
	global_load_dword v67, v[2:3], off
	v_add_co_u32_e32 v2, vcc, s71, v58
	v_readlane_b32 s46, v254, 50
	s_nop 0
	v_addc_co_u32_e32 v3, vcc, 0, v59, vcc
	v_add_co_u32_e32 v4, vcc, s84, v58
	global_load_dword v2, v[2:3], off
	s_nop 0
	v_addc_co_u32_e32 v5, vcc, 0, v59, vcc
	global_load_dword v3, v[4:5], off
	v_add_co_u32_e32 v4, vcc, s85, v58
	v_readlane_b32 s47, v254, 51
	s_nop 0
	v_addc_co_u32_e32 v5, vcc, 0, v59, vcc
	v_add_co_u32_e32 v6, vcc, s86, v58
	global_load_dword v4, v[4:5], off
	s_nop 0
	v_addc_co_u32_e32 v7, vcc, 0, v59, vcc
	global_load_dword v5, v[6:7], off
	v_add_co_u32_e32 v6, vcc, s87, v58
	v_readlane_b32 s48, v254, 52
	s_nop 0
	v_addc_co_u32_e32 v7, vcc, 0, v59, vcc
	v_add_co_u32_e32 v8, vcc, s88, v58
	global_load_dword v6, v[6:7], off
	s_nop 0
	v_addc_co_u32_e32 v9, vcc, 0, v59, vcc
	global_load_dword v7, v[8:9], off
	v_add_co_u32_e32 v8, vcc, s89, v58
	v_readlane_b32 s49, v254, 53
	s_nop 0
	v_addc_co_u32_e32 v9, vcc, 0, v59, vcc
	v_add_co_u32_e32 v10, vcc, s90, v58
	global_load_dword v8, v[8:9], off
	s_nop 0
	v_addc_co_u32_e32 v11, vcc, 0, v59, vcc
	global_load_dword v9, v[10:11], off
	v_add_co_u32_e32 v10, vcc, s91, v58
	s_waitcnt vmcnt(14)
	v_cvt_pk_bf16_f32 v60, v60, v61
	v_addc_co_u32_e32 v11, vcc, 0, v59, vcc
	v_add_co_u32_e32 v12, vcc, s92, v58
	global_load_dword v10, v[10:11], off
	s_nop 0
	v_addc_co_u32_e32 v13, vcc, 0, v59, vcc
	global_load_dword v11, v[12:13], off
	v_add_co_u32_e32 v12, vcc, s93, v58
	s_waitcnt vmcnt(14)
	v_cvt_pk_bf16_f32 v61, v62, v63
	v_addc_co_u32_e32 v13, vcc, 0, v59, vcc
	v_add_co_u32_e32 v14, vcc, s94, v58
	global_load_dword v12, v[12:13], off
	s_nop 0
	v_addc_co_u32_e32 v15, vcc, 0, v59, vcc
	global_load_dword v13, v[14:15], off
	v_add_co_u32_e32 v14, vcc, s95, v58
	s_waitcnt vmcnt(14)
	v_cvt_pk_bf16_f32 v62, v64, v65
	v_addc_co_u32_e32 v15, vcc, 0, v59, vcc
	v_add_co_u32_e32 v16, vcc, s96, v58
	global_load_dword v14, v[14:15], off
	s_nop 0
	v_addc_co_u32_e32 v17, vcc, 0, v59, vcc
	global_load_dword v15, v[16:17], off
	v_add_co_u32_e32 v16, vcc, s97, v58
	s_waitcnt vmcnt(14)
; __device__ __forceinline__ unsigned pk2(float lo, float hi) { typedef float f2_t __attribute__((ext_vector_type(2))); typedef __bf16 b2_t __attribute__((ext_vector_type(2))); const f2_t v = {lo, hi}; return __builtin_bit_cast(unsigned, __builtin_convertvector(v, b2_t)); }
; __device__ __forceinline__ void transpose_item(const float* W, int K, int N, bf16* WT, int mode, int row_off, const float* gain, int item, int lane) {
;     ...
;     const float* src = W + (size_t)k0 * N + n0 + lane;
;     float v[64];
; #pragma unroll
;     for (int i = 0; i < 64; ++i) v[i] = src[(size_t)i * N];
;     if (gain) {
; #pragma unroll
;         for (int i = 0; i < 64; ++i) v[i] *= gain[k0 + i];
;     }
;     bf16* dst = WT + (size_t)(rbase + lane) * K + k0;
; #pragma unroll
;     for (int c = 0; c < 8; ++c) { v4u o; o.x = pk2(v[8 * c], v[8 * c + 1]); o.y = pk2(v[8 * c + 2], v[8 * c + 3]); o.z = pk2(v[8 * c + 4], v[8 * c + 5]); o.w = pk2(v[8 * c + 6], v[8 * c + 7]);
;         *(v4u*)(dst + 8 * c) = o; }
	v_cvt_pk_bf16_f32 v63, v66, v67
	v_addc_co_u32_e32 v17, vcc, 0, v59, vcc
	v_add_co_u32_e32 v18, vcc, s34, v58
	global_load_dword v16, v[16:17], off
	s_nop 0
	v_addc_co_u32_e32 v19, vcc, 0, v59, vcc
	global_load_dword v17, v[18:19], off
	v_add_co_u32_e32 v18, vcc, s13, v58
	v_readlane_b32 s50, v254, 54
	s_nop 0
	v_addc_co_u32_e32 v19, vcc, 0, v59, vcc
	v_add_co_u32_e32 v20, vcc, s16, v58
	global_load_dword v18, v[18:19], off
	s_nop 0
	v_addc_co_u32_e32 v21, vcc, 0, v59, vcc
	global_load_dword v19, v[20:21], off
	v_add_co_u32_e32 v20, vcc, s17, v58
	v_readlane_b32 s51, v254, 55
	s_nop 0
	v_addc_co_u32_e32 v21, vcc, 0, v59, vcc
	v_add_co_u32_e32 v22, vcc, s18, v58
	global_load_dword v20, v[20:21], off
	s_nop 0
	v_addc_co_u32_e32 v23, vcc, 0, v59, vcc
	global_load_dword v21, v[22:23], off
	v_add_co_u32_e32 v22, vcc, s33, v58
	v_readlane_b32 s54, v254, 58
	s_nop 0
	v_addc_co_u32_e32 v23, vcc, 0, v59, vcc
	v_add_co_u32_e32 v24, vcc, s70, v58
	global_load_dword v22, v[22:23], off
	s_nop 0
	v_addc_co_u32_e32 v25, vcc, 0, v59, vcc
	global_load_dword v23, v[24:25], off
	v_add_co_u32_e32 v24, vcc, s4, v58
	v_readlane_b32 s55, v254, 59
	s_nop 0
	v_addc_co_u32_e32 v25, vcc, 0, v59, vcc
	v_add_co_u32_e32 v26, vcc, s5, v58
	global_load_dword v24, v[24:25], off
	s_nop 0
	v_addc_co_u32_e32 v27, vcc, 0, v59, vcc
	global_load_dword v25, v[26:27], off
	v_add_co_u32_e32 v26, vcc, s68, v58
	v_readlane_b32 s56, v254, 60
	s_nop 0
	v_addc_co_u32_e32 v27, vcc, 0, v59, vcc
	v_add_co_u32_e32 v28, vcc, s3, v58
	global_load_dword v26, v[26:27], off
	s_nop 0
	v_addc_co_u32_e32 v29, vcc, 0, v59, vcc
	global_load_dword v27, v[28:29], off
	v_add_co_u32_e32 v28, vcc, s2, v58
	v_readlane_b32 s57, v254, 61
	s_nop 0
	v_addc_co_u32_e32 v29, vcc, 0, v59, vcc
	v_add_co_u32_e32 v30, vcc, s6, v58
	global_load_dword v28, v[28:29], off
	s_nop 0
	v_addc_co_u32_e32 v31, vcc, 0, v59, vcc
	global_load_dword v29, v[30:31], off
	v_add_co_u32_e32 v30, vcc, s7, v58
	v_readlane_b32 s58, v254, 62
	s_nop 0
	v_addc_co_u32_e32 v31, vcc, 0, v59, vcc
	v_add_co_u32_e32 v32, vcc, s76, v58
	global_load_dword v30, v[30:31], off
	s_nop 0
	v_addc_co_u32_e32 v33, vcc, 0, v59, vcc
	global_load_dword v31, v[32:33], off
	v_add_co_u32_e32 v32, vcc, s77, v58
	v_readlane_b32 s59, v254, 63
	s_nop 0
	v_addc_co_u32_e32 v33, vcc, 0, v59, vcc
	v_add_co_u32_e32 v34, vcc, s78, v58
	global_load_dword v32, v[32:33], off
	s_nop 0
	v_addc_co_u32_e32 v35, vcc, 0, v59, vcc
	global_load_dword v33, v[34:35], off
	v_add_co_u32_e32 v34, vcc, s79, v58
	s_nop 1
	v_addc_co_u32_e32 v35, vcc, 0, v59, vcc
	v_add_co_u32_e32 v36, vcc, s19, v58
	global_load_dword v34, v[34:35], off
	s_nop 0
	v_addc_co_u32_e32 v37, vcc, 0, v59, vcc
	global_load_dword v35, v[36:37], off
	v_add_co_u32_e32 v36, vcc, s20, v58
	s_nop 1
	v_addc_co_u32_e32 v37, vcc, 0, v59, vcc
	v_add_co_u32_e32 v38, vcc, s30, v58
	global_load_dword v36, v[36:37], off
	s_nop 0
	v_addc_co_u32_e32 v39, vcc, 0, v59, vcc
	global_load_dword v37, v[38:39], off
	v_add_co_u32_e32 v38, vcc, s31, v58
	s_nop 1
	v_addc_co_u32_e32 v39, vcc, 0, v59, vcc
	v_add_co_u32_e32 v40, vcc, s42, v58
	global_load_dword v38, v[38:39], off
	s_nop 0
	v_addc_co_u32_e32 v41, vcc, 0, v59, vcc
	global_load_dword v39, v[40:41], off
	v_add_co_u32_e32 v40, vcc, s43, v58
	s_nop 1
	v_addc_co_u32_e32 v41, vcc, 0, v59, vcc
	v_add_co_u32_e32 v42, vcc, s26, v58
	global_load_dword v40, v[40:41], off
	s_nop 0
	v_addc_co_u32_e32 v43, vcc, 0, v59, vcc
	global_load_dword v41, v[42:43], off
	v_add_co_u32_e32 v42, vcc, s27, v58
	s_nop 1
	v_addc_co_u32_e32 v43, vcc, 0, v59, vcc
	v_add_co_u32_e32 v44, vcc, s21, v58
	global_load_dword v42, v[42:43], off
	s_nop 0
	v_addc_co_u32_e32 v45, vcc, 0, v59, vcc
	global_load_dword v43, v[44:45], off
	v_add_co_u32_e32 v44, vcc, s22, v58
	s_nop 1
	v_addc_co_u32_e32 v45, vcc, 0, v59, vcc
	v_add_co_u32_e32 v46, vcc, s23, v58
	global_load_dword v44, v[44:45], off
	s_nop 0
	v_addc_co_u32_e32 v47, vcc, 0, v59, vcc
	global_load_dword v45, v[46:47], off
	v_add_co_u32_e32 v46, vcc, s25, v58
	s_nop 1
	v_addc_co_u32_e32 v47, vcc, 0, v59, vcc
	v_add_co_u32_e32 v48, vcc, s29, v58
	global_load_dword v46, v[46:47], off
	s_nop 0
	v_addc_co_u32_e32 v49, vcc, 0, v59, vcc
	global_load_dword v47, v[48:49], off
	v_add_co_u32_e32 v48, vcc, s35, v58
	s_nop 1
	v_addc_co_u32_e32 v49, vcc, 0, v59, vcc
	v_add_co_u32_e32 v50, vcc, s38, v58
	global_load_dword v48, v[48:49], off
	s_nop 0
	v_addc_co_u32_e32 v51, vcc, 0, v59, vcc
	global_load_dword v49, v[50:51], off
	v_add_co_u32_e32 v50, vcc, s39, v58
	s_nop 1
	v_addc_co_u32_e32 v51, vcc, 0, v59, vcc
	v_add_co_u32_e32 v52, vcc, s60, v58
	global_load_dword v50, v[50:51], off
	s_nop 0
	v_addc_co_u32_e32 v53, vcc, 0, v59, vcc
	global_load_dword v51, v[52:53], off
	v_add_co_u32_e32 v52, vcc, s61, v58
	s_nop 1
	v_addc_co_u32_e32 v53, vcc, 0, v59, vcc
	v_add_co_u32_e32 v54, vcc, s62, v58
	global_load_dword v52, v[52:53], off
	s_nop 0
	v_addc_co_u32_e32 v55, vcc, 0, v59, vcc
	global_load_dword v53, v[54:55], off
	v_add_co_u32_e32 v54, vcc, s63, v58
	s_nop 1
	v_addc_co_u32_e32 v55, vcc, 0, v59, vcc
	v_add_co_u32_e32 v56, vcc, s8, v58
	global_load_dword v54, v[54:55], off
	s_nop 0
	v_addc_co_u32_e32 v57, vcc, 0, v59, vcc
	global_load_dword v55, v[56:57], off
	v_add_co_u32_e32 v56, vcc, s9, v58
	s_nop 1
	v_addc_co_u32_e32 v57, vcc, 0, v59, vcc
	v_add_co_u32_e32 v58, vcc, s10, v58
	global_load_dword v56, v[56:57], off
	s_nop 0
	v_addc_co_u32_e32 v59, vcc, 0, v59, vcc
	global_load_dword v57, v[58:59], off
	v_or_b32_e32 v58, s74, v188
	v_mul_u32_u24_e32 v58, 0x1600, v58
	v_lshlrev_b32_e32 v58, 1, v58
	v_mov_b32_e32 v59, v1
	v_lshl_add_u64 v[58:59], s[44:45], 0, v[58:59]
	v_lshl_add_u64 v[58:59], s[66:67], 1, v[58:59]
	v_lshrrev_b32_e32 v200, 6, v189
	v_mul_u32_u24_e32 v201, 0x90, v188
	v_mul_u32_u24_e32 v200, 0x2400, v200
	v_add_u32_e32 v200, v200, v201
	ds_write_b128 v200, v[60:63]
	s_nop 1
	s_mov_b64 s[74:75], 0

; __device__ __forceinline__ unsigned pk2(float lo, float hi) { typedef float f2_t __attribute__((ext_vector_type(2))); typedef __bf16 b2_t __attribute__((ext_vector_type(2))); const f2_t v = {lo, hi}; return __builtin_bit_cast(unsigned, __builtin_convertvector(v, b2_t)); }
; __device__ __forceinline__ void transpose_item(const float* W, int K, int N, bf16* WT, int mode, int row_off, const float* gain, int item, int lane) {
;     ...
;     bf16* dst = WT + (size_t)(rbase + lane) * K + k0;
; #pragma unroll
;     for (int c = 0; c < 8; ++c) { v4u o; o.x = pk2(v[8 * c], v[8 * c + 1]); o.y = pk2(v[8 * c + 2], v[8 * c + 3]); o.z = pk2(v[8 * c + 4], v[8 * c + 5]); o.w = pk2(v[8 * c + 6], v[8 * c + 7]);
;         *(v4u*)(dst + 8 * c) = o; }
.LBB0_312:
	s_lshl_b32 s75, s74, 6
	s_lshl_b32 s74, s74, 7
	s_and_b32 s75, s75, 64
	s_or_b32 s74, s75, s74
	v_or_b32_e32 v58, s74, v188
	v_readlane_b32 s44, v255, 2
	v_lshl_or_b32 v58, v58, 12, v68
	v_mov_b32_e32 v59, v1
	v_readlane_b32 s45, v255, 3
	s_lshl_b32 s66, s66, 1
	s_waitcnt vmcnt(62)
	v_cvt_pk_bf16_f32 v60, v60, v61
	v_lshl_add_u64 v[58:59], s[44:45], 0, v[58:59]
	v_lshl_add_u64 v[58:59], v[58:59], 0, s[66:67]
	s_waitcnt vmcnt(60)
	v_cvt_pk_bf16_f32 v61, v62, v63
	s_waitcnt vmcnt(58)
	v_cvt_pk_bf16_f32 v62, v64, v65
	s_waitcnt vmcnt(56)
	v_cvt_pk_bf16_f32 v63, v66, v67
	v_lshrrev_b32_e32 v200, 6, v189
	v_mul_u32_u24_e32 v201, 0x90, v188
	v_mul_u32_u24_e32 v200, 0x2400, v200
	v_add_u32_e32 v200, v200, v201
	ds_write_b128 v200, v[60:63]
	s_nop 1

; __device__ __forceinline__ unsigned pk2(float lo, float hi) { typedef float f2_t __attribute__((ext_vector_type(2))); typedef __bf16 b2_t __attribute__((ext_vector_type(2))); const f2_t v = {lo, hi}; return __builtin_bit_cast(unsigned, __builtin_convertvector(v, b2_t)); }
; __device__ __forceinline__ void transpose_item(const float* W, int K, int N, bf16* WT, int mode, int row_off, const float* gain, int item, int lane) {
;     ...
;     bf16* dst = WT + (size_t)(rbase + lane) * K + k0;
; #pragma unroll
;     for (int c = 0; c < 8; ++c) { v4u o; o.x = pk2(v[8 * c], v[8 * c + 1]); o.y = pk2(v[8 * c + 2], v[8 * c + 3]); o.z = pk2(v[8 * c + 4], v[8 * c + 5]); o.w = pk2(v[8 * c + 6], v[8 * c + 7]);
;         *(v4u*)(dst + 8 * c) = o; }
.LBB0_317:
	s_lshl_b32 s75, s74, 6
	s_lshl_b32 s74, s74, 7
	s_and_b32 s74, s74, 0x3f00
	s_and_b32 s75, s75, 64
	s_or_b32 s74, s75, s74
	v_or_b32_e32 v58, s74, v188
	v_readlane_b32 s44, v255, 2
	v_lshlrev_b32_e32 v58, 12, v58
	v_mov_b32_e32 v59, v1
	v_readlane_b32 s45, v255, 3
	s_lshl_b32 s66, s66, 1
	s_waitcnt vmcnt(62)
	v_cvt_pk_bf16_f32 v60, v60, v61
	v_lshl_add_u64 v[58:59], s[44:45], 0, v[58:59]
	v_lshl_add_u64 v[58:59], v[58:59], 0, s[66:67]
	s_waitcnt vmcnt(60)
	v_cvt_pk_bf16_f32 v61, v62, v63
	s_waitcnt vmcnt(58)
	v_cvt_pk_bf16_f32 v62, v64, v65
	s_waitcnt vmcnt(56)
	v_cvt_pk_bf16_f32 v63, v66, v67
	v_lshrrev_b32_e32 v200, 6, v189
	v_mul_u32_u24_e32 v201, 0x90, v188
	v_mul_u32_u24_e32 v200, 0x2400, v200
	v_add_u32_e32 v200, v200, v201
	ds_write_b128 v200, v[60:63]
	s_nop 1

; __device__ __forceinline__ void transpose_item(const float* W, int K, int N, bf16* WT, int mode, int row_off, const float* gain, int item, int lane) {
;     const int nblk = N / 64, kb = item / nblk, nb = item % nblk, k0 = 64 * kb, n0 = 64 * nb;
;     const int rbase = (mode == 0) ? (row_off + n0) : ((n0 >> 7) * 256 + (n0 & 127) + row_off);
;     const float* src = W + (size_t)k0 * N + n0 + lane;
;     float v[64];
; #pragma unroll
;     for (int i = 0; i < 64; ++i) v[i] = src[(size_t)i * N];
.LBB0_319:
	s_andn2_b64 vcc, exec, s[74:75]
	s_cbranch_vccnz .LBB0_321
	s_lshl_b32 s66, s81, 4
	s_add_i32 s66, s66, 0x1f800
	s_and_b32 s66, s66, 0x1ffc0
	s_lshl_b32 s74, s80, 6
	s_and_b32 s74, s74, 0x7c0
	s_lshl_b32 s75, s66, 13
	v_readlane_b32 s44, v254, 48
	v_readlane_b32 s45, v254, 49
	s_add_u32 s75, s44, s75
	s_addc_u32 s83, s45, 0
	s_lshl_b32 s82, s74, 2
	s_add_u32 s82, s75, s82
	s_addc_u32 s83, s83, 0
	v_lshl_add_u64 v[58:59], s[82:83], 0, v[0:1]
	s_movk_i32 s44, 0x2000
	s_waitcnt vmcnt(56)
	v_add_co_u32_e32 v2, vcc, s44, v58
	s_movk_i32 s44, 0x4000
	s_waitcnt vmcnt(55)
	v_addc_co_u32_e32 v3, vcc, 0, v59, vcc
	global_load_dword v60, v0, s[82:83]
	global_load_dword v61, v[2:3], off
	v_add_co_u32_e32 v2, vcc, s44, v58
	s_movk_i32 s44, 0x6000
	s_nop 0
	v_addc_co_u32_e32 v3, vcc, 0, v59, vcc
	global_load_dword v62, v[2:3], off
	v_add_co_u32_e32 v2, vcc, s44, v58
	s_mov_b32 s44, 0x8000
	s_nop 0
	v_addc_co_u32_e32 v3, vcc, 0, v59, vcc
	global_load_dword v63, v[2:3], off
	v_add_co_u32_e32 v2, vcc, s44, v58
	s_mov_b32 s44, 0xa000
	s_nop 0
	v_addc_co_u32_e32 v3, vcc, 0, v59, vcc
	global_load_dword v64, v[2:3], off
	v_add_co_u32_e32 v2, vcc, s44, v58
	v_readlane_b32 s44, v255, 8
	s_nop 0
	v_addc_co_u32_e32 v3, vcc, 0, v59, vcc
	global_load_dword v65, v[2:3], off
	v_add_co_u32_e32 v2, vcc, s41, v58
	v_readlane_b32 s45, v255, 9
	s_nop 0
	v_addc_co_u32_e32 v3, vcc, 0, v59, vcc
	global_load_dword v66, v[2:3], off
	v_add_co_u32_e32 v2, vcc, s69, v58
	s_lshl_b32 s66, s66, 1
	s_nop 0
	v_addc_co_u32_e32 v3, vcc, 0, v59, vcc
	global_load_dword v67, v[2:3], off
	v_add_co_u32_e32 v2, vcc, s71, v58
	v_readlane_b32 s46, v254, 50
	s_nop 0
	v_addc_co_u32_e32 v3, vcc, 0, v59, vcc
	s_waitcnt vmcnt(62)
	v_add_co_u32_e32 v4, vcc, s84, v58
	global_load_dword v2, v[2:3], off
	s_waitcnt vmcnt(62)
	v_addc_co_u32_e32 v5, vcc, 0, v59, vcc
	global_load_dword v3, v[4:5], off
	v_add_co_u32_e32 v4, vcc, s85, v58
	v_readlane_b32 s47, v254, 51
	s_nop 0
	v_addc_co_u32_e32 v5, vcc, 0, v59, vcc
	s_waitcnt vmcnt(62)
	v_add_co_u32_e32 v6, vcc, s86, v58
	global_load_dword v4, v[4:5], off
	s_waitcnt vmcnt(62)
	v_addc_co_u32_e32 v7, vcc, 0, v59, vcc
	global_load_dword v5, v[6:7], off
	v_add_co_u32_e32 v6, vcc, s87, v58
	v_readlane_b32 s48, v254, 52
	s_nop 0
	v_addc_co_u32_e32 v7, vcc, 0, v59, vcc
	s_waitcnt vmcnt(62)
	v_add_co_u32_e32 v8, vcc, s88, v58
	global_load_dword v6, v[6:7], off
	s_waitcnt vmcnt(62)
	v_addc_co_u32_e32 v9, vcc, 0, v59, vcc
	global_load_dword v7, v[8:9], off
	v_add_co_u32_e32 v8, vcc, s89, v58
	v_readlane_b32 s49, v254, 53
	s_nop 0
	v_addc_co_u32_e32 v9, vcc, 0, v59, vcc
	s_waitcnt vmcnt(62)
	v_add_co_u32_e32 v10, vcc, s90, v58
	global_load_dword v8, v[8:9], off
	s_waitcnt vmcnt(62)
	v_addc_co_u32_e32 v11, vcc, 0, v59, vcc
	global_load_dword v9, v[10:11], off
	v_add_co_u32_e32 v10, vcc, s91, v58
	s_waitcnt vmcnt(14)
	v_cvt_pk_bf16_f32 v60, v60, v61
	v_addc_co_u32_e32 v11, vcc, 0, v59, vcc
	v_add_co_u32_e32 v12, vcc, s92, v58
	global_load_dword v10, v[10:11], off
	s_nop 0
	v_addc_co_u32_e32 v13, vcc, 0, v59, vcc
	global_load_dword v11, v[12:13], off
	v_add_co_u32_e32 v12, vcc, s93, v58
	s_waitcnt vmcnt(14)
	v_cvt_pk_bf16_f32 v61, v62, v63
	v_addc_co_u32_e32 v13, vcc, 0, v59, vcc
	v_add_co_u32_e32 v14, vcc, s94, v58
	global_load_dword v12, v[12:13], off
	s_nop 0
	v_addc_co_u32_e32 v15, vcc, 0, v59, vcc
	global_load_dword v13, v[14:15], off
	v_add_co_u32_e32 v14, vcc, s95, v58
	s_waitcnt vmcnt(14)
	v_cvt_pk_bf16_f32 v62, v64, v65
	v_addc_co_u32_e32 v15, vcc, 0, v59, vcc
	v_add_co_u32_e32 v16, vcc, s96, v58
	global_load_dword v14, v[14:15], off
	s_nop 0
	v_addc_co_u32_e32 v17, vcc, 0, v59, vcc
	global_load_dword v15, v[16:17], off
	v_add_co_u32_e32 v16, vcc, s97, v58
	s_waitcnt vmcnt(14)
; __device__ __forceinline__ unsigned pk2(float lo, float hi) { typedef float f2_t __attribute__((ext_vector_type(2))); typedef __bf16 b2_t __attribute__((ext_vector_type(2))); const f2_t v = {lo, hi}; return __builtin_bit_cast(unsigned, __builtin_convertvector(v, b2_t)); }
; __device__ __forceinline__ void transpose_item(const float* W, int K, int N, bf16* WT, int mode, int row_off, const float* gain, int item, int lane) {
;     ...
;     const float* src = W + (size_t)k0 * N + n0 + lane;
;     float v[64];
; #pragma unroll
;     for (int i = 0; i < 64; ++i) v[i] = src[(size_t)i * N];
;     if (gain) {
; #pragma unroll
;         for (int i = 0; i < 64; ++i) v[i] *= gain[k0 + i];
;     }
;     bf16* dst = WT + (size_t)(rbase + lane) * K + k0;
; #pragma unroll
;     for (int c = 0; c < 8; ++c) { v4u o; o.x = pk2(v[8 * c], v[8 * c + 1]); o.y = pk2(v[8 * c + 2], v[8 * c + 3]); o.z = pk2(v[8 * c + 4], v[8 * c + 5]); o.w = pk2(v[8 * c + 6], v[8 * c + 7]);
;         *(v4u*)(dst + 8 * c) = o; }
	v_cvt_pk_bf16_f32 v63, v66, v67
	v_addc_co_u32_e32 v17, vcc, 0, v59, vcc
	v_add_co_u32_e32 v18, vcc, s34, v58
	global_load_dword v16, v[16:17], off
	s_nop 0
	v_addc_co_u32_e32 v19, vcc, 0, v59, vcc
	global_load_dword v17, v[18:19], off
	v_add_co_u32_e32 v18, vcc, s13, v58
	v_readlane_b32 s50, v254, 54
	s_nop 0
	v_addc_co_u32_e32 v19, vcc, 0, v59, vcc
	v_add_co_u32_e32 v20, vcc, s16, v58
	global_load_dword v18, v[18:19], off
	s_nop 0
	v_addc_co_u32_e32 v21, vcc, 0, v59, vcc
	global_load_dword v19, v[20:21], off
	v_add_co_u32_e32 v20, vcc, s17, v58
	v_readlane_b32 s51, v254, 55
	s_nop 0
	v_addc_co_u32_e32 v21, vcc, 0, v59, vcc
	v_add_co_u32_e32 v22, vcc, s18, v58
	global_load_dword v20, v[20:21], off
	s_nop 0
	v_addc_co_u32_e32 v23, vcc, 0, v59, vcc
	global_load_dword v21, v[22:23], off
	v_add_co_u32_e32 v22, vcc, s33, v58
	v_readlane_b32 s52, v254, 56
	s_nop 0
	v_addc_co_u32_e32 v23, vcc, 0, v59, vcc
	v_add_co_u32_e32 v24, vcc, s70, v58
	global_load_dword v22, v[22:23], off
	s_nop 0
	v_addc_co_u32_e32 v25, vcc, 0, v59, vcc
	global_load_dword v23, v[24:25], off
	v_add_co_u32_e32 v24, vcc, s4, v58
	v_readlane_b32 s53, v254, 57
	s_nop 0
	v_addc_co_u32_e32 v25, vcc, 0, v59, vcc
	v_add_co_u32_e32 v26, vcc, s5, v58
	global_load_dword v24, v[24:25], off
	s_nop 0
	v_addc_co_u32_e32 v27, vcc, 0, v59, vcc
	global_load_dword v25, v[26:27], off
	v_add_co_u32_e32 v26, vcc, s68, v58
	v_readlane_b32 s54, v254, 58
	s_nop 0
	v_addc_co_u32_e32 v27, vcc, 0, v59, vcc
	v_add_co_u32_e32 v28, vcc, s3, v58
	global_load_dword v26, v[26:27], off
	s_nop 0
	v_addc_co_u32_e32 v29, vcc, 0, v59, vcc
	global_load_dword v27, v[28:29], off
	v_add_co_u32_e32 v28, vcc, s2, v58
	v_readlane_b32 s55, v254, 59
	s_nop 0
	v_addc_co_u32_e32 v29, vcc, 0, v59, vcc
	v_add_co_u32_e32 v30, vcc, s6, v58
	global_load_dword v28, v[28:29], off
	s_nop 0
	v_addc_co_u32_e32 v31, vcc, 0, v59, vcc
	global_load_dword v29, v[30:31], off
	v_add_co_u32_e32 v30, vcc, s7, v58
	v_readlane_b32 s56, v254, 60
	s_nop 0
	v_addc_co_u32_e32 v31, vcc, 0, v59, vcc
	v_add_co_u32_e32 v32, vcc, s76, v58
	global_load_dword v30, v[30:31], off
	s_nop 0
	v_addc_co_u32_e32 v33, vcc, 0, v59, vcc
	global_load_dword v31, v[32:33], off
	v_add_co_u32_e32 v32, vcc, s77, v58
	v_readlane_b32 s57, v254, 61
	s_nop 0
	v_addc_co_u32_e32 v33, vcc, 0, v59, vcc
	v_add_co_u32_e32 v34, vcc, s78, v58
	global_load_dword v32, v[32:33], off
	s_nop 0
	v_addc_co_u32_e32 v35, vcc, 0, v59, vcc
	global_load_dword v33, v[34:35], off
	v_add_co_u32_e32 v34, vcc, s79, v58
	v_readlane_b32 s58, v254, 62
	s_nop 0
	v_addc_co_u32_e32 v35, vcc, 0, v59, vcc
	v_add_co_u32_e32 v36, vcc, s19, v58
	global_load_dword v34, v[34:35], off
	s_nop 0
	v_addc_co_u32_e32 v37, vcc, 0, v59, vcc
	global_load_dword v35, v[36:37], off
	v_add_co_u32_e32 v36, vcc, s20, v58
	v_readlane_b32 s59, v254, 63
	s_nop 0
	v_addc_co_u32_e32 v37, vcc, 0, v59, vcc
	v_add_co_u32_e32 v38, vcc, s30, v58
	global_load_dword v36, v[36:37], off
	s_nop 0
	v_addc_co_u32_e32 v39, vcc, 0, v59, vcc
	global_load_dword v37, v[38:39], off
	v_add_co_u32_e32 v38, vcc, s31, v58
	s_nop 1
	v_addc_co_u32_e32 v39, vcc, 0, v59, vcc
	v_add_co_u32_e32 v40, vcc, s42, v58
	global_load_dword v38, v[38:39], off
	s_nop 0
	v_addc_co_u32_e32 v41, vcc, 0, v59, vcc
	global_load_dword v39, v[40:41], off
	v_add_co_u32_e32 v40, vcc, s43, v58
	s_nop 1
	v_addc_co_u32_e32 v41, vcc, 0, v59, vcc
	v_add_co_u32_e32 v42, vcc, s26, v58
	global_load_dword v40, v[40:41], off
	s_nop 0
	v_addc_co_u32_e32 v43, vcc, 0, v59, vcc
	global_load_dword v41, v[42:43], off
	v_add_co_u32_e32 v42, vcc, s27, v58
	s_nop 1
	v_addc_co_u32_e32 v43, vcc, 0, v59, vcc
	v_add_co_u32_e32 v44, vcc, s21, v58
	global_load_dword v42, v[42:43], off
	s_nop 0
	v_addc_co_u32_e32 v45, vcc, 0, v59, vcc
	global_load_dword v43, v[44:45], off
	v_add_co_u32_e32 v44, vcc, s22, v58
	s_nop 1
	v_addc_co_u32_e32 v45, vcc, 0, v59, vcc
	v_add_co_u32_e32 v46, vcc, s23, v58
	global_load_dword v44, v[44:45], off
	s_nop 0
	v_addc_co_u32_e32 v47, vcc, 0, v59, vcc
	global_load_dword v45, v[46:47], off
	v_add_co_u32_e32 v46, vcc, s25, v58
	s_nop 1
	v_addc_co_u32_e32 v47, vcc, 0, v59, vcc
	v_add_co_u32_e32 v48, vcc, s29, v58
	global_load_dword v46, v[46:47], off
	s_nop 0
	v_addc_co_u32_e32 v49, vcc, 0, v59, vcc
	global_load_dword v47, v[48:49], off
	v_add_co_u32_e32 v48, vcc, s35, v58
	s_nop 1
	v_addc_co_u32_e32 v49, vcc, 0, v59, vcc
	v_add_co_u32_e32 v50, vcc, s38, v58
	global_load_dword v48, v[48:49], off
	s_nop 0
	v_addc_co_u32_e32 v51, vcc, 0, v59, vcc
	global_load_dword v49, v[50:51], off
	v_add_co_u32_e32 v50, vcc, s39, v58
	s_nop 1
	v_addc_co_u32_e32 v51, vcc, 0, v59, vcc
	v_add_co_u32_e32 v52, vcc, s60, v58
	global_load_dword v50, v[50:51], off
	s_nop 0
	v_addc_co_u32_e32 v53, vcc, 0, v59, vcc
	global_load_dword v51, v[52:53], off
	v_add_co_u32_e32 v52, vcc, s61, v58
	s_nop 1
	v_addc_co_u32_e32 v53, vcc, 0, v59, vcc
	v_add_co_u32_e32 v54, vcc, s62, v58
	global_load_dword v52, v[52:53], off
	s_nop 0
	v_addc_co_u32_e32 v55, vcc, 0, v59, vcc
	global_load_dword v53, v[54:55], off
	v_add_co_u32_e32 v54, vcc, s63, v58
	s_nop 1
	v_addc_co_u32_e32 v55, vcc, 0, v59, vcc
	v_add_co_u32_e32 v56, vcc, s8, v58
	global_load_dword v54, v[54:55], off
	s_nop 0
	v_addc_co_u32_e32 v57, vcc, 0, v59, vcc
	global_load_dword v55, v[56:57], off
	v_add_co_u32_e32 v56, vcc, s9, v58
	s_nop 1
	v_addc_co_u32_e32 v57, vcc, 0, v59, vcc
	v_add_co_u32_e32 v58, vcc, s10, v58
	global_load_dword v56, v[56:57], off
	s_nop 0
	v_addc_co_u32_e32 v59, vcc, 0, v59, vcc
	global_load_dword v57, v[58:59], off
	v_or_b32_e32 v58, s74, v188
	v_lshlrev_b32_e32 v58, 12, v58
	v_mov_b32_e32 v59, v1
	v_lshl_add_u64 v[58:59], s[44:45], 0, v[58:59]
	v_lshl_add_u64 v[58:59], v[58:59], 0, s[66:67]
	v_lshrrev_b32_e32 v200, 6, v189
	v_mul_u32_u24_e32 v201, 0x90, v188
	v_mul_u32_u24_e32 v200, 0x2400, v200
	v_add_u32_e32 v200, v200, v201
	ds_write_b128 v200, v[60:63]
	s_nop 1

; __device__ __forceinline__ void transpose_item(const float* W, int K, int N, bf16* WT, int mode, int row_off, const float* gain, int item, int lane) {
;     const int nblk = N / 64, kb = item / nblk, nb = item % nblk, k0 = 64 * kb, n0 = 64 * nb;
;     const int rbase = (mode == 0) ? (row_off + n0) : ((n0 >> 7) * 256 + (n0 & 127) + row_off);
;     const float* src = W + (size_t)k0 * N + n0 + lane;
;     float v[64];
; #pragma unroll
;     for (int i = 0; i < 64; ++i) v[i] = src[(size_t)i * N];
.LBB0_322:
	s_andn2_b64 vcc, exec, s[74:75]
	s_cbranch_vccnz .LBB0_324
	s_lshl_b32 s66, s81, 4
	s_add_i32 s66, s66, 0x1fc00
	s_and_b32 s66, s66, 0x1ffc0
	s_lshl_b32 s74, s80, 6
	v_readlane_b32 s44, v254, 23
	s_and_b32 s74, s74, 0x7c0
	s_lshl_b32 s75, s66, 13
	v_readlane_b32 s54, v254, 33
	v_readlane_b32 s55, v254, 34
	s_add_u32 s75, s54, s75
	s_addc_u32 s81, s55, 0
	s_lshl_b32 s82, s74, 2
	s_add_u32 s82, s75, s82
	s_addc_u32 s83, s81, 0
	v_lshl_add_u64 v[58:59], s[82:83], 0, v[0:1]
	s_movk_i32 s44, 0x2000
	s_waitcnt vmcnt(56)
	v_add_co_u32_e32 v2, vcc, s44, v58
	s_movk_i32 s44, 0x4000
	s_waitcnt vmcnt(55)
	v_addc_co_u32_e32 v3, vcc, 0, v59, vcc
	global_load_dword v60, v0, s[82:83]
	global_load_dword v61, v[2:3], off
	v_add_co_u32_e32 v2, vcc, s44, v58
	s_movk_i32 s44, 0x6000
	s_nop 0
	v_addc_co_u32_e32 v3, vcc, 0, v59, vcc
	global_load_dword v62, v[2:3], off
	v_add_co_u32_e32 v2, vcc, s44, v58
	s_mov_b32 s44, 0x8000
	s_nop 0
	v_addc_co_u32_e32 v3, vcc, 0, v59, vcc
	global_load_dword v63, v[2:3], off
	v_add_co_u32_e32 v2, vcc, s44, v58
	s_mov_b32 s44, 0xa000
	s_nop 0
	v_addc_co_u32_e32 v3, vcc, 0, v59, vcc
	global_load_dword v64, v[2:3], off
	v_add_co_u32_e32 v2, vcc, s44, v58
	s_lshl_b32 s66, s66, 1
	s_nop 0
	v_addc_co_u32_e32 v3, vcc, 0, v59, vcc
	global_load_dword v65, v[2:3], off
	v_add_co_u32_e32 v2, vcc, s41, v58
	v_readlane_b32 s45, v254, 24
	s_nop 0
	v_addc_co_u32_e32 v3, vcc, 0, v59, vcc
	global_load_dword v66, v[2:3], off
	v_add_co_u32_e32 v2, vcc, s69, v58
	v_readlane_b32 s46, v254, 25
	s_nop 0
	v_addc_co_u32_e32 v3, vcc, 0, v59, vcc
	global_load_dword v67, v[2:3], off
	v_add_co_u32_e32 v2, vcc, s71, v58
	v_readlane_b32 s47, v254, 26
	s_nop 0
	v_addc_co_u32_e32 v3, vcc, 0, v59, vcc
	s_waitcnt vmcnt(62)
	v_add_co_u32_e32 v4, vcc, s84, v58
	global_load_dword v2, v[2:3], off
	s_waitcnt vmcnt(62)
	v_addc_co_u32_e32 v5, vcc, 0, v59, vcc
	global_load_dword v3, v[4:5], off
	v_add_co_u32_e32 v4, vcc, s85, v58
	v_readlane_b32 s48, v254, 27
	s_nop 0
	v_addc_co_u32_e32 v5, vcc, 0, v59, vcc
	s_waitcnt vmcnt(62)
	v_add_co_u32_e32 v6, vcc, s86, v58
	global_load_dword v4, v[4:5], off
	s_waitcnt vmcnt(62)
	v_addc_co_u32_e32 v7, vcc, 0, v59, vcc
	global_load_dword v5, v[6:7], off
	v_add_co_u32_e32 v6, vcc, s87, v58
	v_readlane_b32 s49, v254, 28
	s_nop 0
	v_addc_co_u32_e32 v7, vcc, 0, v59, vcc
	s_waitcnt vmcnt(62)
	v_add_co_u32_e32 v8, vcc, s88, v58
	global_load_dword v6, v[6:7], off
	s_waitcnt vmcnt(62)
	v_addc_co_u32_e32 v9, vcc, 0, v59, vcc
	global_load_dword v7, v[8:9], off
	v_add_co_u32_e32 v8, vcc, s89, v58
	v_readlane_b32 s50, v254, 29
	s_nop 0
	v_addc_co_u32_e32 v9, vcc, 0, v59, vcc
	s_waitcnt vmcnt(62)
	v_add_co_u32_e32 v10, vcc, s90, v58
	global_load_dword v8, v[8:9], off
	s_waitcnt vmcnt(62)
	v_addc_co_u32_e32 v11, vcc, 0, v59, vcc
	global_load_dword v9, v[10:11], off
	v_add_co_u32_e32 v10, vcc, s91, v58
	s_waitcnt vmcnt(14)
	v_cvt_pk_bf16_f32 v60, v60, v61
	v_addc_co_u32_e32 v11, vcc, 0, v59, vcc
	v_add_co_u32_e32 v12, vcc, s92, v58
	global_load_dword v10, v[10:11], off
	s_nop 0
	v_addc_co_u32_e32 v13, vcc, 0, v59, vcc
	global_load_dword v11, v[12:13], off
	v_add_co_u32_e32 v12, vcc, s93, v58
	s_waitcnt vmcnt(14)
	v_cvt_pk_bf16_f32 v61, v62, v63
	v_addc_co_u32_e32 v13, vcc, 0, v59, vcc
	v_add_co_u32_e32 v14, vcc, s94, v58
	global_load_dword v12, v[12:13], off
	s_nop 0
	v_addc_co_u32_e32 v15, vcc, 0, v59, vcc
	global_load_dword v13, v[14:15], off
	v_add_co_u32_e32 v14, vcc, s95, v58
	s_waitcnt vmcnt(14)
	v_cvt_pk_bf16_f32 v62, v64, v65
	v_addc_co_u32_e32 v15, vcc, 0, v59, vcc
	v_add_co_u32_e32 v16, vcc, s96, v58
	global_load_dword v14, v[14:15], off
	s_nop 0
	v_addc_co_u32_e32 v17, vcc, 0, v59, vcc
	global_load_dword v15, v[16:17], off
	v_add_co_u32_e32 v16, vcc, s97, v58
	s_waitcnt vmcnt(14)
; __device__ __forceinline__ unsigned pk2(float lo, float hi) { typedef float f2_t __attribute__((ext_vector_type(2))); typedef __bf16 b2_t __attribute__((ext_vector_type(2))); const f2_t v = {lo, hi}; return __builtin_bit_cast(unsigned, __builtin_convertvector(v, b2_t)); }
; __device__ __forceinline__ void transpose_item(const float* W, int K, int N, bf16* WT, int mode, int row_off, const float* gain, int item, int lane) {
;     ...
;     const float* src = W + (size_t)k0 * N + n0 + lane;
;     float v[64];
; #pragma unroll
;     for (int i = 0; i < 64; ++i) v[i] = src[(size_t)i * N];
;     if (gain) {
; #pragma unroll
;         for (int i = 0; i < 64; ++i) v[i] *= gain[k0 + i];
;     }
;     bf16* dst = WT + (size_t)(rbase + lane) * K + k0;
; #pragma unroll
;     for (int c = 0; c < 8; ++c) { v4u o; o.x = pk2(v[8 * c], v[8 * c + 1]); o.y = pk2(v[8 * c + 2], v[8 * c + 3]); o.z = pk2(v[8 * c + 4], v[8 * c + 5]); o.w = pk2(v[8 * c + 6], v[8 * c + 7]);
;         *(v4u*)(dst + 8 * c) = o; }
	v_cvt_pk_bf16_f32 v63, v66, v67
	v_addc_co_u32_e32 v17, vcc, 0, v59, vcc
	v_add_co_u32_e32 v18, vcc, s34, v58
	global_load_dword v16, v[16:17], off
	s_nop 0
	v_addc_co_u32_e32 v19, vcc, 0, v59, vcc
	global_load_dword v17, v[18:19], off
	v_add_co_u32_e32 v18, vcc, s13, v58
	v_readlane_b32 s51, v254, 30
	s_nop 0
	v_addc_co_u32_e32 v19, vcc, 0, v59, vcc
	v_add_co_u32_e32 v20, vcc, s16, v58
	global_load_dword v18, v[18:19], off
	s_nop 0
	v_addc_co_u32_e32 v21, vcc, 0, v59, vcc
	global_load_dword v19, v[20:21], off
	v_add_co_u32_e32 v20, vcc, s17, v58
	v_readlane_b32 s52, v254, 31
	s_nop 0
	v_addc_co_u32_e32 v21, vcc, 0, v59, vcc
	v_add_co_u32_e32 v22, vcc, s18, v58
	global_load_dword v20, v[20:21], off
	s_nop 0
	v_addc_co_u32_e32 v23, vcc, 0, v59, vcc
	global_load_dword v21, v[22:23], off
	v_add_co_u32_e32 v22, vcc, s33, v58
	v_readlane_b32 s53, v254, 32
	s_nop 0
	v_addc_co_u32_e32 v23, vcc, 0, v59, vcc
	v_add_co_u32_e32 v24, vcc, s70, v58
	global_load_dword v22, v[22:23], off
	s_nop 0
	v_addc_co_u32_e32 v25, vcc, 0, v59, vcc
	global_load_dword v23, v[24:25], off
	v_add_co_u32_e32 v24, vcc, s4, v58
	v_readlane_b32 s56, v254, 35
	s_nop 0
	v_addc_co_u32_e32 v25, vcc, 0, v59, vcc
	v_add_co_u32_e32 v26, vcc, s5, v58
	global_load_dword v24, v[24:25], off
	s_nop 0
	v_addc_co_u32_e32 v27, vcc, 0, v59, vcc
	global_load_dword v25, v[26:27], off
	v_add_co_u32_e32 v26, vcc, s68, v58
	v_readlane_b32 s57, v254, 36
	s_nop 0
	v_addc_co_u32_e32 v27, vcc, 0, v59, vcc
	v_add_co_u32_e32 v28, vcc, s3, v58
	global_load_dword v26, v[26:27], off
	s_nop 0
	v_addc_co_u32_e32 v29, vcc, 0, v59, vcc
	global_load_dword v27, v[28:29], off
	v_add_co_u32_e32 v28, vcc, s2, v58
	v_readlane_b32 s58, v254, 37
	s_nop 0
	v_addc_co_u32_e32 v29, vcc, 0, v59, vcc
	v_add_co_u32_e32 v30, vcc, s6, v58
	global_load_dword v28, v[28:29], off
	s_nop 0
	v_addc_co_u32_e32 v31, vcc, 0, v59, vcc
	global_load_dword v29, v[30:31], off
	v_add_co_u32_e32 v30, vcc, s7, v58
	v_readlane_b32 s59, v254, 38
	s_nop 0
	v_addc_co_u32_e32 v31, vcc, 0, v59, vcc
	v_add_co_u32_e32 v32, vcc, s76, v58
	global_load_dword v30, v[30:31], off
	s_nop 0
	v_addc_co_u32_e32 v33, vcc, 0, v59, vcc
	global_load_dword v31, v[32:33], off
	v_add_co_u32_e32 v32, vcc, s77, v58
	s_nop 1
	v_addc_co_u32_e32 v33, vcc, 0, v59, vcc
	v_add_co_u32_e32 v34, vcc, s78, v58
	global_load_dword v32, v[32:33], off
	s_nop 0
	v_addc_co_u32_e32 v35, vcc, 0, v59, vcc
	global_load_dword v33, v[34:35], off
	v_add_co_u32_e32 v34, vcc, s79, v58
	s_nop 1
	v_addc_co_u32_e32 v35, vcc, 0, v59, vcc
	v_add_co_u32_e32 v36, vcc, s19, v58
	global_load_dword v34, v[34:35], off
	s_nop 0
	v_addc_co_u32_e32 v37, vcc, 0, v59, vcc
	global_load_dword v35, v[36:37], off
	v_add_co_u32_e32 v36, vcc, s20, v58
	s_nop 1
	v_addc_co_u32_e32 v37, vcc, 0, v59, vcc
	v_add_co_u32_e32 v38, vcc, s30, v58
	global_load_dword v36, v[36:37], off
	s_nop 0
	v_addc_co_u32_e32 v39, vcc, 0, v59, vcc
	global_load_dword v37, v[38:39], off
	v_add_co_u32_e32 v38, vcc, s31, v58
	s_nop 1
	v_addc_co_u32_e32 v39, vcc, 0, v59, vcc
	v_add_co_u32_e32 v40, vcc, s42, v58
	global_load_dword v38, v[38:39], off
	s_nop 0
	v_addc_co_u32_e32 v41, vcc, 0, v59, vcc
	global_load_dword v39, v[40:41], off
	v_add_co_u32_e32 v40, vcc, s43, v58
	s_nop 1
	v_addc_co_u32_e32 v41, vcc, 0, v59, vcc
	v_add_co_u32_e32 v42, vcc, s26, v58
	global_load_dword v40, v[40:41], off
	s_nop 0
	v_addc_co_u32_e32 v43, vcc, 0, v59, vcc
	global_load_dword v41, v[42:43], off
	v_add_co_u32_e32 v42, vcc, s27, v58
	s_nop 1
	v_addc_co_u32_e32 v43, vcc, 0, v59, vcc
	v_add_co_u32_e32 v44, vcc, s21, v58
	global_load_dword v42, v[42:43], off
	s_nop 0
	v_addc_co_u32_e32 v45, vcc, 0, v59, vcc
	global_load_dword v43, v[44:45], off
	v_add_co_u32_e32 v44, vcc, s22, v58
	s_nop 1
	v_addc_co_u32_e32 v45, vcc, 0, v59, vcc
	v_add_co_u32_e32 v46, vcc, s23, v58
	global_load_dword v44, v[44:45], off
	s_nop 0
	v_addc_co_u32_e32 v47, vcc, 0, v59, vcc
	global_load_dword v45, v[46:47], off
	v_add_co_u32_e32 v46, vcc, s25, v58
	s_nop 1
	v_addc_co_u32_e32 v47, vcc, 0, v59, vcc
	v_add_co_u32_e32 v48, vcc, s29, v58
	global_load_dword v46, v[46:47], off
	s_nop 0
	v_addc_co_u32_e32 v49, vcc, 0, v59, vcc
	global_load_dword v47, v[48:49], off
	v_add_co_u32_e32 v48, vcc, s35, v58
	s_nop 1
	v_addc_co_u32_e32 v49, vcc, 0, v59, vcc
	v_add_co_u32_e32 v50, vcc, s38, v58
	global_load_dword v48, v[48:49], off
	s_nop 0
	v_addc_co_u32_e32 v51, vcc, 0, v59, vcc
	global_load_dword v49, v[50:51], off
	v_add_co_u32_e32 v50, vcc, s39, v58
	s_nop 1
	v_addc_co_u32_e32 v51, vcc, 0, v59, vcc
	v_add_co_u32_e32 v52, vcc, s60, v58
	global_load_dword v50, v[50:51], off
	s_nop 0
	v_addc_co_u32_e32 v53, vcc, 0, v59, vcc
	global_load_dword v51, v[52:53], off
	v_add_co_u32_e32 v52, vcc, s61, v58
	s_nop 1
	v_addc_co_u32_e32 v53, vcc, 0, v59, vcc
	v_add_co_u32_e32 v54, vcc, s62, v58
	global_load_dword v52, v[52:53], off
	s_nop 0
	v_addc_co_u32_e32 v55, vcc, 0, v59, vcc
	global_load_dword v53, v[54:55], off
	v_add_co_u32_e32 v54, vcc, s63, v58
	s_nop 1
	v_addc_co_u32_e32 v55, vcc, 0, v59, vcc
	v_add_co_u32_e32 v56, vcc, s8, v58
	global_load_dword v54, v[54:55], off
	s_nop 0
	v_addc_co_u32_e32 v57, vcc, 0, v59, vcc
	global_load_dword v55, v[56:57], off
	v_add_co_u32_e32 v56, vcc, s9, v58
	s_nop 1
	v_addc_co_u32_e32 v57, vcc, 0, v59, vcc
	v_add_co_u32_e32 v58, vcc, s10, v58
	global_load_dword v56, v[56:57], off
	s_nop 0
	v_addc_co_u32_e32 v59, vcc, 0, v59, vcc
	global_load_dword v57, v[58:59], off
	v_or_b32_e32 v58, s74, v188
	v_lshlrev_b32_e32 v58, 11, v58
	v_mov_b32_e32 v59, v1
	v_lshl_add_u64 v[58:59], s[14:15], 0, v[58:59]
	v_lshl_add_u64 v[58:59], v[58:59], 0, s[66:67]
	v_lshrrev_b32_e32 v200, 6, v189
	v_mul_u32_u24_e32 v201, 0x90, v188
	v_mul_u32_u24_e32 v200, 0x2400, v200
	v_add_u32_e32 v200, v200, v201
	ds_write_b128 v200, v[60:63]
	s_nop 1

; __device__ __forceinline__ void transpose_item(const float* W, int K, int N, bf16* WT, int mode, int row_off, const float* gain, int item, int lane) {
;     const int nblk = N / 64, kb = item / nblk, nb = item % nblk, k0 = 64 * kb, n0 = 64 * nb;
;     const int rbase = (mode == 0) ? (row_off + n0) : ((n0 >> 7) * 256 + (n0 & 127) + row_off);
;     const float* src = W + (size_t)k0 * N + n0 + lane;
;     float v[64];
; #pragma unroll
;     for (int i = 0; i < 64; ++i) v[i] = src[(size_t)i * N];
.LBB0_325:
	s_andn2_b64 vcc, exec, s[74:75]
	s_cbranch_vccnz .LBB0_296
	s_ashr_i32 s66, s80, 31
	s_lshr_b32 s66, s66, 27
	s_add_i32 s66, s80, s66
	s_and_b32 s74, s66, 0x3ffffe0
	s_lshl_b32 s66, s66, 1
	s_sub_i32 s75, s80, s74
	s_and_b32 s74, s66, 0xffffffc0
	s_lshl_b32 s80, s75, 6
	s_ashr_i32 s75, s74, 31
	v_readlane_b32 s44, v254, 23
	s_lshl_b64 s[82:83], s[74:75], 13
	v_readlane_b32 s52, v254, 31
	v_readlane_b32 s53, v254, 32
	s_add_u32 s66, s52, s82
	s_addc_u32 vcc_lo, s53, s83
	s_ashr_i32 s81, s80, 31
	s_lshl_b64 s[82:83], s[80:81], 2
	s_add_u32 s82, s66, s82
	s_addc_u32 s83, vcc_lo, s83
	v_lshl_add_u64 v[58:59], s[82:83], 0, v[0:1]
	s_movk_i32 s44, 0x2000
	s_waitcnt vmcnt(56)
	v_add_co_u32_e32 v2, vcc, s44, v58
	s_movk_i32 s44, 0x4000
	s_waitcnt vmcnt(55)
	v_addc_co_u32_e32 v3, vcc, 0, v59, vcc
	global_load_dword v60, v0, s[82:83]
	global_load_dword v61, v[2:3], off
	v_add_co_u32_e32 v2, vcc, s44, v58
	s_movk_i32 s44, 0x6000
	s_nop 0
	v_addc_co_u32_e32 v3, vcc, 0, v59, vcc
	global_load_dword v62, v[2:3], off
	v_add_co_u32_e32 v2, vcc, s44, v58
	s_mov_b32 s44, 0x8000
	s_nop 0
	v_addc_co_u32_e32 v3, vcc, 0, v59, vcc
	global_load_dword v63, v[2:3], off
	v_add_co_u32_e32 v2, vcc, s44, v58
	s_mov_b32 s44, 0xa000
	s_nop 0
	v_addc_co_u32_e32 v3, vcc, 0, v59, vcc
	global_load_dword v64, v[2:3], off
	v_add_co_u32_e32 v2, vcc, s44, v58
	v_readlane_b32 s45, v254, 24
	s_nop 0
	v_addc_co_u32_e32 v3, vcc, 0, v59, vcc
	global_load_dword v65, v[2:3], off
	v_add_co_u32_e32 v2, vcc, s41, v58
	v_readlane_b32 s46, v254, 25
	s_nop 0
	v_addc_co_u32_e32 v3, vcc, 0, v59, vcc
	global_load_dword v66, v[2:3], off
	v_add_co_u32_e32 v2, vcc, s69, v58
	v_readlane_b32 s47, v254, 26
	s_nop 0
	v_addc_co_u32_e32 v3, vcc, 0, v59, vcc
	global_load_dword v67, v[2:3], off
	v_add_co_u32_e32 v2, vcc, s71, v58
	v_readlane_b32 s48, v254, 27
	s_nop 0
	v_addc_co_u32_e32 v3, vcc, 0, v59, vcc
	s_waitcnt vmcnt(62)
	v_add_co_u32_e32 v4, vcc, s84, v58
	global_load_dword v2, v[2:3], off
	s_waitcnt vmcnt(62)
	v_addc_co_u32_e32 v5, vcc, 0, v59, vcc
	global_load_dword v3, v[4:5], off
	v_add_co_u32_e32 v4, vcc, s85, v58
	v_readlane_b32 s49, v254, 28
	s_nop 0
	v_addc_co_u32_e32 v5, vcc, 0, v59, vcc
	s_waitcnt vmcnt(62)
	v_add_co_u32_e32 v6, vcc, s86, v58
	global_load_dword v4, v[4:5], off
	s_waitcnt vmcnt(62)
	v_addc_co_u32_e32 v7, vcc, 0, v59, vcc
	global_load_dword v5, v[6:7], off
	v_add_co_u32_e32 v6, vcc, s87, v58
	v_readlane_b32 s50, v254, 29
	s_nop 0
	v_addc_co_u32_e32 v7, vcc, 0, v59, vcc
	s_waitcnt vmcnt(62)
	v_add_co_u32_e32 v8, vcc, s88, v58
	global_load_dword v6, v[6:7], off
	s_waitcnt vmcnt(62)
	v_addc_co_u32_e32 v9, vcc, 0, v59, vcc
	global_load_dword v7, v[8:9], off
	v_add_co_u32_e32 v8, vcc, s89, v58
	v_readlane_b32 s51, v254, 30
	s_nop 0
	v_addc_co_u32_e32 v9, vcc, 0, v59, vcc
	s_waitcnt vmcnt(62)
	v_add_co_u32_e32 v10, vcc, s90, v58
	global_load_dword v8, v[8:9], off
	s_waitcnt vmcnt(62)
	v_addc_co_u32_e32 v11, vcc, 0, v59, vcc
	global_load_dword v9, v[10:11], off
	v_add_co_u32_e32 v10, vcc, s91, v58
	s_waitcnt vmcnt(14)
	v_cvt_pk_bf16_f32 v60, v60, v61
	v_addc_co_u32_e32 v11, vcc, 0, v59, vcc
	v_add_co_u32_e32 v12, vcc, s92, v58
	global_load_dword v10, v[10:11], off
	s_nop 0
	v_addc_co_u32_e32 v13, vcc, 0, v59, vcc
	global_load_dword v11, v[12:13], off
	v_add_co_u32_e32 v12, vcc, s93, v58
	s_waitcnt vmcnt(14)
	v_cvt_pk_bf16_f32 v61, v62, v63
	v_addc_co_u32_e32 v13, vcc, 0, v59, vcc
	v_add_co_u32_e32 v14, vcc, s94, v58
	global_load_dword v12, v[12:13], off
	s_nop 0
	v_addc_co_u32_e32 v15, vcc, 0, v59, vcc
	global_load_dword v13, v[14:15], off
	v_add_co_u32_e32 v14, vcc, s95, v58
	s_waitcnt vmcnt(14)
	v_cvt_pk_bf16_f32 v62, v64, v65
	v_addc_co_u32_e32 v15, vcc, 0, v59, vcc
	v_add_co_u32_e32 v16, vcc, s96, v58
	global_load_dword v14, v[14:15], off
	s_nop 0
	v_addc_co_u32_e32 v17, vcc, 0, v59, vcc
	global_load_dword v15, v[16:17], off
	v_add_co_u32_e32 v16, vcc, s97, v58
	s_waitcnt vmcnt(14)
; __device__ __forceinline__ unsigned pk2(float lo, float hi) { typedef float f2_t __attribute__((ext_vector_type(2))); typedef __bf16 b2_t __attribute__((ext_vector_type(2))); const f2_t v = {lo, hi}; return __builtin_bit_cast(unsigned, __builtin_convertvector(v, b2_t)); }
; __device__ __forceinline__ void transpose_item(const float* W, int K, int N, bf16* WT, int mode, int row_off, const float* gain, int item, int lane) {
;     ...
;     const float* src = W + (size_t)k0 * N + n0 + lane;
;     float v[64];
; #pragma unroll
;     for (int i = 0; i < 64; ++i) v[i] = src[(size_t)i * N];
;     if (gain) {
; #pragma unroll
;         for (int i = 0; i < 64; ++i) v[i] *= gain[k0 + i];
;     }
;     bf16* dst = WT + (size_t)(rbase + lane) * K + k0;
; #pragma unroll
;     for (int c = 0; c < 8; ++c) { v4u o; o.x = pk2(v[8 * c], v[8 * c + 1]); o.y = pk2(v[8 * c + 2], v[8 * c + 3]); o.z = pk2(v[8 * c + 4], v[8 * c + 5]); o.w = pk2(v[8 * c + 6], v[8 * c + 7]);
;         *(v4u*)(dst + 8 * c) = o; }
	v_cvt_pk_bf16_f32 v63, v66, v67
	v_addc_co_u32_e32 v17, vcc, 0, v59, vcc
	v_add_co_u32_e32 v18, vcc, s34, v58
	global_load_dword v16, v[16:17], off
	s_nop 0
	v_addc_co_u32_e32 v19, vcc, 0, v59, vcc
	global_load_dword v17, v[18:19], off
	v_add_co_u32_e32 v18, vcc, s13, v58
	v_readlane_b32 s54, v254, 33
	s_nop 0
	v_addc_co_u32_e32 v19, vcc, 0, v59, vcc
	v_add_co_u32_e32 v20, vcc, s16, v58
	global_load_dword v18, v[18:19], off
	s_nop 0
	v_addc_co_u32_e32 v21, vcc, 0, v59, vcc
	global_load_dword v19, v[20:21], off
	v_add_co_u32_e32 v20, vcc, s17, v58
	v_readlane_b32 s55, v254, 34
	s_nop 0
	v_addc_co_u32_e32 v21, vcc, 0, v59, vcc
	v_add_co_u32_e32 v22, vcc, s18, v58
	global_load_dword v20, v[20:21], off
	s_nop 0
	v_addc_co_u32_e32 v23, vcc, 0, v59, vcc
	global_load_dword v21, v[22:23], off
	v_add_co_u32_e32 v22, vcc, s33, v58
	v_readlane_b32 s56, v254, 35
	s_nop 0
	v_addc_co_u32_e32 v23, vcc, 0, v59, vcc
	v_add_co_u32_e32 v24, vcc, s70, v58
	global_load_dword v22, v[22:23], off
	s_nop 0
	v_addc_co_u32_e32 v25, vcc, 0, v59, vcc
	global_load_dword v23, v[24:25], off
	v_add_co_u32_e32 v24, vcc, s4, v58
	v_readlane_b32 s57, v254, 36
	s_nop 0
	v_addc_co_u32_e32 v25, vcc, 0, v59, vcc
	v_add_co_u32_e32 v26, vcc, s5, v58
	global_load_dword v24, v[24:25], off
	s_nop 0
	v_addc_co_u32_e32 v27, vcc, 0, v59, vcc
	global_load_dword v25, v[26:27], off
	v_add_co_u32_e32 v26, vcc, s68, v58
	v_readlane_b32 s58, v254, 37
	s_nop 0
	v_addc_co_u32_e32 v27, vcc, 0, v59, vcc
	v_add_co_u32_e32 v28, vcc, s3, v58
	global_load_dword v26, v[26:27], off
	s_nop 0
	v_addc_co_u32_e32 v29, vcc, 0, v59, vcc
	global_load_dword v27, v[28:29], off
	v_add_co_u32_e32 v28, vcc, s2, v58
	v_readlane_b32 s59, v254, 38
	s_nop 0
	v_addc_co_u32_e32 v29, vcc, 0, v59, vcc
	v_add_co_u32_e32 v30, vcc, s6, v58
	global_load_dword v28, v[28:29], off
	s_nop 0
	v_addc_co_u32_e32 v31, vcc, 0, v59, vcc
	global_load_dword v29, v[30:31], off
	v_add_co_u32_e32 v30, vcc, s7, v58
	s_nop 1
	v_addc_co_u32_e32 v31, vcc, 0, v59, vcc
	v_add_co_u32_e32 v32, vcc, s76, v58
	global_load_dword v30, v[30:31], off
	s_nop 0
	v_addc_co_u32_e32 v33, vcc, 0, v59, vcc
	global_load_dword v31, v[32:33], off
	v_add_co_u32_e32 v32, vcc, s77, v58
	s_nop 1
	v_addc_co_u32_e32 v33, vcc, 0, v59, vcc
	v_add_co_u32_e32 v34, vcc, s78, v58
	global_load_dword v32, v[32:33], off
	s_nop 0
	v_addc_co_u32_e32 v35, vcc, 0, v59, vcc
	global_load_dword v33, v[34:35], off
	v_add_co_u32_e32 v34, vcc, s79, v58
	s_nop 1
	v_addc_co_u32_e32 v35, vcc, 0, v59, vcc
	v_add_co_u32_e32 v36, vcc, s19, v58
	global_load_dword v34, v[34:35], off
	s_nop 0
	v_addc_co_u32_e32 v37, vcc, 0, v59, vcc
	global_load_dword v35, v[36:37], off
	v_add_co_u32_e32 v36, vcc, s20, v58
	s_nop 1
	v_addc_co_u32_e32 v37, vcc, 0, v59, vcc
	v_add_co_u32_e32 v38, vcc, s30, v58
	global_load_dword v36, v[36:37], off
	s_nop 0
	v_addc_co_u32_e32 v39, vcc, 0, v59, vcc
	global_load_dword v37, v[38:39], off
	v_add_co_u32_e32 v38, vcc, s31, v58
	s_nop 1
	v_addc_co_u32_e32 v39, vcc, 0, v59, vcc
	v_add_co_u32_e32 v40, vcc, s42, v58
	global_load_dword v38, v[38:39], off
	s_nop 0
	v_addc_co_u32_e32 v41, vcc, 0, v59, vcc
	global_load_dword v39, v[40:41], off
	v_add_co_u32_e32 v40, vcc, s43, v58
	s_nop 1
	v_addc_co_u32_e32 v41, vcc, 0, v59, vcc
	v_add_co_u32_e32 v42, vcc, s26, v58
	global_load_dword v40, v[40:41], off
	s_nop 0
	v_addc_co_u32_e32 v43, vcc, 0, v59, vcc
	global_load_dword v41, v[42:43], off
	v_add_co_u32_e32 v42, vcc, s27, v58
	s_nop 1
	v_addc_co_u32_e32 v43, vcc, 0, v59, vcc
	v_add_co_u32_e32 v44, vcc, s21, v58
	global_load_dword v42, v[42:43], off
	s_nop 0
	v_addc_co_u32_e32 v45, vcc, 0, v59, vcc
	global_load_dword v43, v[44:45], off
	v_add_co_u32_e32 v44, vcc, s22, v58
	s_nop 1
	v_addc_co_u32_e32 v45, vcc, 0, v59, vcc
	v_add_co_u32_e32 v46, vcc, s23, v58
	global_load_dword v44, v[44:45], off
	s_nop 0
	v_addc_co_u32_e32 v47, vcc, 0, v59, vcc
	global_load_dword v45, v[46:47], off
	v_add_co_u32_e32 v46, vcc, s25, v58
	s_nop 1
	v_addc_co_u32_e32 v47, vcc, 0, v59, vcc
	v_add_co_u32_e32 v48, vcc, s29, v58
	global_load_dword v46, v[46:47], off
	s_nop 0
	v_addc_co_u32_e32 v49, vcc, 0, v59, vcc
	global_load_dword v47, v[48:49], off
	v_add_co_u32_e32 v48, vcc, s35, v58
	s_nop 1
	v_addc_co_u32_e32 v49, vcc, 0, v59, vcc
	v_add_co_u32_e32 v50, vcc, s38, v58
	global_load_dword v48, v[48:49], off
	s_nop 0
	v_addc_co_u32_e32 v51, vcc, 0, v59, vcc
	global_load_dword v49, v[50:51], off
	v_add_co_u32_e32 v50, vcc, s39, v58
	s_nop 1
	v_addc_co_u32_e32 v51, vcc, 0, v59, vcc
	v_add_co_u32_e32 v52, vcc, s60, v58
	global_load_dword v50, v[50:51], off
	s_nop 0
	v_addc_co_u32_e32 v53, vcc, 0, v59, vcc
	global_load_dword v51, v[52:53], off
	v_add_co_u32_e32 v52, vcc, s61, v58
	s_nop 1
	v_addc_co_u32_e32 v53, vcc, 0, v59, vcc
	v_add_co_u32_e32 v54, vcc, s62, v58
	global_load_dword v52, v[52:53], off
	s_nop 0
	v_addc_co_u32_e32 v55, vcc, 0, v59, vcc
	global_load_dword v53, v[54:55], off
	v_add_co_u32_e32 v54, vcc, s63, v58
	s_nop 1
	v_addc_co_u32_e32 v55, vcc, 0, v59, vcc
	v_add_co_u32_e32 v56, vcc, s8, v58
	global_load_dword v54, v[54:55], off
	s_nop 0
	v_addc_co_u32_e32 v57, vcc, 0, v59, vcc
	global_load_dword v55, v[56:57], off
	v_add_co_u32_e32 v56, vcc, s9, v58
	s_nop 1
	v_addc_co_u32_e32 v57, vcc, 0, v59, vcc
	v_add_co_u32_e32 v58, vcc, s10, v58
	global_load_dword v56, v[56:57], off
	s_nop 0
	v_addc_co_u32_e32 v59, vcc, 0, v59, vcc
	global_load_dword v57, v[58:59], off
	v_or_b32_e32 v58, s80, v188
	v_ashrrev_i32_e32 v59, 31, v58
	v_lshlrev_b64 v[58:59], 11, v[58:59]
	v_lshl_add_u64 v[58:59], s[64:65], 0, v[58:59]
	v_lshl_add_u64 v[58:59], s[74:75], 1, v[58:59]
	v_lshrrev_b32_e32 v200, 6, v189
	v_mul_u32_u24_e32 v201, 0x90, v188
	v_mul_u32_u24_e32 v200, 0x2400, v200
	v_add_u32_e32 v200, v200, v201
	ds_write_b128 v200, v[60:63]
	s_nop 1
	s_branch .LBB0_296
